# attention: lane^32 shuffle index without the redundant range select (4 VALU fewer per key tile)
# baseline (speedup 1.0000x reference)
.LBB0_110:
	s_nop 10
	v_max_f32_e32 v214, v65, v65
	v_max_f32_e32 v215, v64, v64
	v_max_f32_e32 v214, v215, v214
	v_max3_f32 v214, v214, v66, v67
	v_max3_f32 v214, v214, v68, v69
	v_max3_f32 v214, v214, v70, v71
	v_max3_f32 v214, v214, v72, v73
	v_xor_b32_e32 v215, 32, v208
	v_max3_f32 v214, v214, v74, v75
	v_max3_f32 v214, v214, v76, v77
	v_max3_f32 v214, v214, v78, v79
	v_lshlrev_b32_e32 v230, 2, v215
	ds_bpermute_b32 v215, v230, v214
	s_waitcnt lgkmcnt(0)
	v_max3_f32 v234, v228, v214, v215
	v_sub_f32_e32 v64, v64, v234
	v_exp_f32_e32 v235, v64
	v_sub_f32_e32 v65, v65, v234
	v_exp_f32_e32 v65, v65
	v_sub_f32_e32 v66, v66, v234
	v_exp_f32_e32 v66, v66
	v_sub_f32_e32 v67, v67, v234
	v_exp_f32_e32 v67, v67
	v_sub_f32_e32 v68, v68, v234
	v_add_f32_e32 v214, 0, v235
	v_exp_f32_e32 v68, v68
	v_sub_f32_e32 v69, v69, v234
	v_sub_f32_e32 v64, v228, v234
	v_add_f32_e32 v214, v65, v214
	v_exp_f32_e32 v228, v69
	v_sub_f32_e32 v69, v70, v234
	v_add_f32_e32 v214, v66, v214
	v_exp_f32_e32 v236, v69
	v_sub_f32_e32 v69, v71, v234
	v_add_f32_e32 v214, v67, v214
	v_exp_f32_e32 v237, v69
	v_sub_f32_e32 v69, v72, v234
	v_add_f32_e32 v214, v68, v214
	v_exp_f32_e32 v69, v69
	v_add_f32_e32 v70, v228, v214
	v_add_f32_e32 v70, v236, v70
	v_add_f32_e32 v70, v237, v70
	v_add_f32_e32 v214, v69, v70
	v_sub_f32_e32 v70, v73, v234
	v_exp_f32_e32 v70, v70
	v_sub_f32_e32 v71, v74, v234
	v_exp_f32_e32 v71, v71
	v_sub_f32_e32 v72, v75, v234
	v_exp_f32_e32 v72, v72
	v_sub_f32_e32 v73, v76, v234
	v_exp_f32_e32 v73, v73
	v_add_f32_e32 v74, v70, v214
	v_add_f32_e32 v74, v71, v74
	v_add_f32_e32 v74, v72, v74
	v_add_f32_e32 v214, v73, v74
	v_sub_f32_e32 v74, v77, v234
	v_exp_f32_e32 v74, v74
	v_sub_f32_e32 v75, v78, v234
	v_exp_f32_e32 v75, v75
	v_sub_f32_e32 v76, v79, v234
	v_exp_f32_e32 v76, v76
	v_add_f32_e32 v77, v74, v214
	v_add_f32_e32 v77, v75, v77
	v_exp_f32_e32 v64, v64
	v_add_f32_e32 v77, v76, v77
	ds_bpermute_b32 v78, v230, v77
	v_cmp_neq_f32_e32 vcc, 1.0, v64
	s_cbranch_vccz .LBB0_112
	v_pk_mul_f32 v[62:63], v[62:63], v[64:65] op_sel_hi:[1,0]
	v_pk_mul_f32 v[60:61], v[60:61], v[64:65] op_sel_hi:[1,0]
	v_pk_mul_f32 v[58:59], v[58:59], v[64:65] op_sel_hi:[1,0]
	v_pk_mul_f32 v[56:57], v[56:57], v[64:65] op_sel_hi:[1,0]
	v_pk_mul_f32 v[54:55], v[54:55], v[64:65] op_sel_hi:[1,0]
	v_pk_mul_f32 v[52:53], v[52:53], v[64:65] op_sel_hi:[1,0]
	v_pk_mul_f32 v[50:51], v[50:51], v[64:65] op_sel_hi:[1,0]
	v_pk_mul_f32 v[48:49], v[48:49], v[64:65] op_sel_hi:[1,0]
	v_pk_mul_f32 v[46:47], v[46:47], v[64:65] op_sel_hi:[1,0]
	v_pk_mul_f32 v[44:45], v[44:45], v[64:65] op_sel_hi:[1,0]
	v_pk_mul_f32 v[42:43], v[42:43], v[64:65] op_sel_hi:[1,0]
	v_pk_mul_f32 v[40:41], v[40:41], v[64:65] op_sel_hi:[1,0]
	v_pk_mul_f32 v[38:39], v[38:39], v[64:65] op_sel_hi:[1,0]
	v_pk_mul_f32 v[36:37], v[36:37], v[64:65] op_sel_hi:[1,0]
	v_pk_mul_f32 v[34:35], v[34:35], v[64:65] op_sel_hi:[1,0]
	v_pk_mul_f32 v[32:33], v[32:33], v[64:65] op_sel_hi:[1,0]
	v_pk_mul_f32 v[30:31], v[30:31], v[64:65] op_sel_hi:[1,0]
	v_pk_mul_f32 v[28:29], v[28:29], v[64:65] op_sel_hi:[1,0]
	v_pk_mul_f32 v[26:27], v[26:27], v[64:65] op_sel_hi:[1,0]
	v_pk_mul_f32 v[24:25], v[24:25], v[64:65] op_sel_hi:[1,0]
	v_pk_mul_f32 v[22:23], v[22:23], v[64:65] op_sel_hi:[1,0]
	v_pk_mul_f32 v[20:21], v[20:21], v[64:65] op_sel_hi:[1,0]
	v_pk_mul_f32 v[18:19], v[18:19], v[64:65] op_sel_hi:[1,0]
	v_pk_mul_f32 v[16:17], v[16:17], v[64:65] op_sel_hi:[1,0]
	v_pk_mul_f32 v[14:15], v[14:15], v[64:65] op_sel_hi:[1,0]
	v_pk_mul_f32 v[12:13], v[12:13], v[64:65] op_sel_hi:[1,0]
	v_pk_mul_f32 v[10:11], v[10:11], v[64:65] op_sel_hi:[1,0]
	v_pk_mul_f32 v[8:9], v[8:9], v[64:65] op_sel_hi:[1,0]
	v_pk_mul_f32 v[6:7], v[6:7], v[64:65] op_sel_hi:[1,0]
	v_pk_mul_f32 v[4:5], v[4:5], v[64:65] op_sel_hi:[1,0]
	v_pk_mul_f32 v[2:3], v[2:3], v[64:65] op_sel_hi:[1,0]
	v_pk_mul_f32 v[0:1], v[0:1], v[64:65] op_sel_hi:[1,0]

.LBB0_149:
	s_nop 10
	v_max_f32_e32 v214, v65, v65
	v_max_f32_e32 v215, v64, v64
	v_max_f32_e32 v214, v215, v214
	v_max3_f32 v214, v214, v66, v67
	v_max3_f32 v214, v214, v68, v69
	v_max3_f32 v214, v214, v70, v71
	v_max3_f32 v214, v214, v72, v73
	v_xor_b32_e32 v215, 32, v208
	v_max3_f32 v214, v214, v74, v75
	v_max3_f32 v214, v214, v76, v77
	v_max3_f32 v214, v214, v78, v79
	v_lshlrev_b32_e32 v238, 2, v215
	ds_bpermute_b32 v215, v238, v214
	v_mov_b32_e32 v248, v218
	s_waitcnt lgkmcnt(0)
	v_max3_f32 v242, v236, v214, v215
	v_sub_f32_e32 v64, v64, v242
	v_exp_f32_e32 v243, v64
	v_sub_f32_e32 v65, v65, v242
	v_exp_f32_e32 v65, v65
	v_sub_f32_e32 v66, v66, v242
	v_exp_f32_e32 v66, v66
	v_sub_f32_e32 v67, v67, v242
	v_exp_f32_e32 v67, v67
	v_sub_f32_e32 v68, v68, v242
	v_add_f32_e32 v214, 0, v243
	v_exp_f32_e32 v68, v68
	v_sub_f32_e32 v69, v69, v242
	v_sub_f32_e32 v64, v236, v242
	v_add_f32_e32 v214, v65, v214
	v_exp_f32_e32 v236, v69
	v_sub_f32_e32 v69, v70, v242
	v_add_f32_e32 v214, v66, v214
	v_exp_f32_e32 v244, v69
	v_sub_f32_e32 v69, v71, v242
	v_add_f32_e32 v214, v67, v214
	v_exp_f32_e32 v245, v69
	v_sub_f32_e32 v69, v72, v242
	v_add_f32_e32 v214, v68, v214
	v_exp_f32_e32 v69, v69
	v_add_f32_e32 v70, v236, v214
	v_add_f32_e32 v70, v244, v70
	v_add_f32_e32 v70, v245, v70
	v_add_f32_e32 v214, v69, v70
	v_sub_f32_e32 v70, v73, v242
	v_exp_f32_e32 v70, v70
	v_sub_f32_e32 v71, v74, v242
	v_exp_f32_e32 v71, v71
	v_sub_f32_e32 v72, v75, v242
	v_exp_f32_e32 v72, v72
	v_sub_f32_e32 v73, v76, v242
	v_exp_f32_e32 v73, v73
	v_add_f32_e32 v74, v70, v214
	v_add_f32_e32 v74, v71, v74
	v_add_f32_e32 v74, v72, v74
	v_add_f32_e32 v214, v73, v74
	v_sub_f32_e32 v74, v77, v242
	v_exp_f32_e32 v74, v74
	v_sub_f32_e32 v75, v78, v242
	v_exp_f32_e32 v75, v75
	v_sub_f32_e32 v76, v79, v242
	v_exp_f32_e32 v76, v76
	v_add_f32_e32 v77, v74, v214
	v_add_f32_e32 v77, v75, v77
	v_exp_f32_e32 v64, v64
	v_add_f32_e32 v77, v76, v77
	ds_bpermute_b32 v78, v238, v77
	v_cmp_neq_f32_e32 vcc, 1.0, v64
	s_cbranch_vccz .LBB0_151
	v_pk_mul_f32 v[62:63], v[62:63], v[64:65] op_sel_hi:[1,0]
	v_pk_mul_f32 v[60:61], v[60:61], v[64:65] op_sel_hi:[1,0]
	v_pk_mul_f32 v[58:59], v[58:59], v[64:65] op_sel_hi:[1,0]
	v_pk_mul_f32 v[56:57], v[56:57], v[64:65] op_sel_hi:[1,0]
	v_pk_mul_f32 v[54:55], v[54:55], v[64:65] op_sel_hi:[1,0]
	v_pk_mul_f32 v[52:53], v[52:53], v[64:65] op_sel_hi:[1,0]
	v_pk_mul_f32 v[50:51], v[50:51], v[64:65] op_sel_hi:[1,0]
	v_pk_mul_f32 v[48:49], v[48:49], v[64:65] op_sel_hi:[1,0]
	v_pk_mul_f32 v[46:47], v[46:47], v[64:65] op_sel_hi:[1,0]
	v_pk_mul_f32 v[44:45], v[44:45], v[64:65] op_sel_hi:[1,0]
	v_pk_mul_f32 v[42:43], v[42:43], v[64:65] op_sel_hi:[1,0]
	v_pk_mul_f32 v[40:41], v[40:41], v[64:65] op_sel_hi:[1,0]
	v_pk_mul_f32 v[38:39], v[38:39], v[64:65] op_sel_hi:[1,0]
	v_pk_mul_f32 v[36:37], v[36:37], v[64:65] op_sel_hi:[1,0]
	v_pk_mul_f32 v[34:35], v[34:35], v[64:65] op_sel_hi:[1,0]
	v_pk_mul_f32 v[32:33], v[32:33], v[64:65] op_sel_hi:[1,0]
	v_pk_mul_f32 v[30:31], v[30:31], v[64:65] op_sel_hi:[1,0]
	v_pk_mul_f32 v[28:29], v[28:29], v[64:65] op_sel_hi:[1,0]
	v_pk_mul_f32 v[26:27], v[26:27], v[64:65] op_sel_hi:[1,0]
	v_pk_mul_f32 v[24:25], v[24:25], v[64:65] op_sel_hi:[1,0]
	v_pk_mul_f32 v[22:23], v[22:23], v[64:65] op_sel_hi:[1,0]
	v_pk_mul_f32 v[20:21], v[20:21], v[64:65] op_sel_hi:[1,0]
	v_pk_mul_f32 v[18:19], v[18:19], v[64:65] op_sel_hi:[1,0]
	v_pk_mul_f32 v[16:17], v[16:17], v[64:65] op_sel_hi:[1,0]
	v_pk_mul_f32 v[14:15], v[14:15], v[64:65] op_sel_hi:[1,0]
	v_pk_mul_f32 v[12:13], v[12:13], v[64:65] op_sel_hi:[1,0]
	v_pk_mul_f32 v[10:11], v[10:11], v[64:65] op_sel_hi:[1,0]
	v_pk_mul_f32 v[8:9], v[8:9], v[64:65] op_sel_hi:[1,0]
	v_pk_mul_f32 v[6:7], v[6:7], v[64:65] op_sel_hi:[1,0]
	v_pk_mul_f32 v[4:5], v[4:5], v[64:65] op_sel_hi:[1,0]
	v_pk_mul_f32 v[2:3], v[2:3], v[64:65] op_sel_hi:[1,0]
	v_pk_mul_f32 v[0:1], v[0:1], v[64:65] op_sel_hi:[1,0]
